# P7: three workgroup groups visit (prompt, sample, sample) items in rotated order so the HBM-bound sample items overlap compute-bound prompt items
# speedup vs baseline: 1.0219x; 1.0028x over previous
.LBB0_1048:
	v_readlane_b32 s0, v246, 4
	v_readlane_b32 s1, v246, 5
	s_cmp_lt_i32 s0, 8
	s_cselect_b64 s[0:1], -1, 0
	s_and_b64 s[2:3], s[0:1], s[2:3]
	s_andn2_b64 vcc, exec, s[2:3]
	s_cbranch_vccnz .LBB0_1061
	s_cmpk_gt_i32 s30, 0x2ff
	s_cbranch_scc1 .LBB0_1060
	v_and_b32_e32 v106, 15, v202
	v_mov_b32_e32 v2, 0x8000
	v_readlane_b32 s8, v246, 0
	v_lshrrev_b32_e32 v108, 4, v202
	v_and_or_b32 v122, v202, 7, v2
	v_mul_u32_u24_e32 v2, 0x110, v106
	v_and_b32_e32 v3, 48, v202
	v_add3_u32 v123, s8, v2, v3
	v_lshlrev_b32_e32 v2, 2, v108
	v_bfe_u32 v3, v202, 2, 2
	v_or_b32_e32 v4, v2, v3
	v_lshlrev_b32_e32 v5, 3, v202
	s_add_i32 s2, s8, 0x11000
	v_mul_u32_u24_e32 v4, 0x110, v4
	v_and_b32_e32 v5, 24, v5
	v_lshlrev_b32_e32 v0, 4, v106
	v_add3_u32 v124, s2, v4, v5
	v_add_u32_e32 v4, 0x200, v202
	v_add_u32_e32 v109, s8, v0
	v_lshrrev_b32_e32 v125, 4, v4
	v_add_u32_e32 v4, 0x600, v202
	s_add_u32 s8, s22, 0x195cc000
	v_lshrrev_b32_e32 v127, 4, v4
	v_add_u32_e32 v4, 0xa00, v202
	s_addc_u32 s9, s23, 0
	v_lshrrev_b32_e32 v129, 4, v4
	v_add_u32_e32 v4, 0xe00, v202
	s_add_u32 s10, s22, 0x18fc4000
	v_lshrrev_b32_e32 v131, 4, v4
	v_bfe_u32 v4, v202, 4, 2
	s_addc_u32 s11, s23, 0
	v_lshl_or_b32 v3, v4, 2, v3
	s_add_u32 s12, s22, 0x13aa4000
	v_mul_u32_u24_e32 v3, 0x110, v3
	s_addc_u32 s13, s23, 0
	v_add_u32_e32 v110, s2, v0
	v_and_b32_e32 v0, 8, v202
	v_add3_u32 v133, s2, v3, v5
	s_add_u32 s14, s22, 0x190cc000
	v_lshrrev_b32_e32 v3, 2, v202
	v_lshlrev_b32_e32 v107, 3, v106
	v_cmp_eq_u32_e64 s[6:7], 0, v0
	v_lshlrev_b32_e32 v0, 3, v108
	v_readlane_b32 s36, v246, 38
	s_addc_u32 s15, s23, 0
	v_and_b32_e32 v44, 0x3ffffff0, v3
	v_readlane_b32 s18, v246, 1
	v_mov_b32_e32 v3, 0x13aa4080
	v_lshl_or_b32 v111, v108, 9, v107
	s_waitcnt lgkmcnt(0)
	v_mul_u32_u24_e32 v1, 0x110, v108
	v_or_b32_e32 v113, 64, v108
	v_or_b32_e32 v116, 0x80, v108
	v_or_b32_e32 v119, 0xc0, v108
	v_mov_b32_e32 v41, 0
	v_lshlrev_b32_e32 v40, 5, v106
	v_readlane_b32 s40, v246, 42
	v_readlane_b32 s41, v246, 43
	s_add_u32 s16, s22, 0x192cc000
	v_readlane_b32 s19, v246, 2
	v_lshl_or_b32 v46, v4, 3, v3
	v_mov_b32_e32 v3, 0x195cc080
	v_lshlrev_b32_e32 v50, 1, v0
	v_mbcnt_lo_u32_b32 v0, -1, 0
	v_add_u32_e32 v112, 0x4000, v111
	v_lshl_or_b32 v114, v113, 9, v107
	v_add_u32_e32 v115, 0xc000, v111
	v_lshl_or_b32 v117, v116, 9, v107
	v_add_u32_e32 v118, 0x14000, v111
	v_lshl_or_b32 v120, v119, 9, v107
	v_add_u32_e32 v121, 0x1c000, v111
	v_cmp_gt_u32_e64 s[4:5], 64, v202
	s_mov_b32 s3, 0
	v_mul_u32_u24_e32 v126, 0x110, v125
	v_mul_u32_u24_e32 v128, 0x110, v127
	v_mul_u32_u24_e32 v130, 0x110, v129
	v_mul_u32_u24_e32 v132, 0x110, v131
	v_lshl_add_u64 v[42:43], s[40:41], 0, v[40:41]
	s_addc_u32 s17, s23, 0
	v_mov_b32_e32 v45, v41
	s_lshl_b32 s28, s72, 9
	s_lshl_b32 s29, s18, 9
	v_mov_b32_e32 v47, v41
	v_lshl_or_b32 v48, v4, 4, v3
	v_mov_b32_e32 v49, v41
	v_add_u32_e32 v134, v109, v1
	v_add_u32_e32 v135, v110, v1
	v_mov_b32_e32 v136, 0x358637bd
	s_mov_b32 s30, 0xf149f2ca
	v_lshlrev_b32_e32 v52, 1, v2
	s_mov_b64 s[18:19], 0x200
	s_mov_b64 s[24:25], 0x20000
	v_mbcnt_hi_u32_b32 v137, -1, v0
	v_mov_b32_e32 v138, 0x42000
	s_mov_b32 s31, s72
	s_lshr_b32 s26, s72, 3
	s_mul_i32 s27, s26, 11
	s_lshr_b32 s27, s27, 5
	s_mul_i32 s27, s27, 3
	s_sub_i32 s26, s26, s27
	s_lshl_b32 s26, s26, 8
	s_add_i32 s31, s31, s26
	s_lshl_b32 s28, s31, 9
	v_readlane_b32 s37, v246, 39
	v_readlane_b32 s38, v246, 40
	v_readlane_b32 s39, v246, 41
	v_readlane_b32 s42, v246, 44
	v_readlane_b32 s43, v246, 45
	v_readlane_b32 s44, v246, 46
	v_readlane_b32 s45, v246, 47
	v_readlane_b32 s46, v246, 48
	v_readlane_b32 s47, v246, 49
	v_readlane_b32 s48, v246, 50
	v_readlane_b32 s49, v246, 51
	v_readlane_b32 s50, v246, 52
	v_readlane_b32 s51, v246, 53
	s_branch .LBB0_1052
.LBB0_1051:
	v_readlane_b32 s26, v246, 1
	s_nop 0
	s_add_i32 s31, s31, s26
	s_add_i32 s28, s28, s29
	s_cmpk_lt_i32 s31, 0x300
	s_cbranch_scc1 .Lp7_nowrap
	s_addk_i32 s31, 0xfd00
	s_add_i32 s28, s28, 0xfffa0000
.Lp7_nowrap:
	s_lshr_b32 s26, s72, 3
	s_mul_i32 s27, s26, 11
	s_lshr_b32 s27, s27, 5
	s_mul_i32 s27, s27, 3
	s_sub_i32 s26, s26, s27
	s_lshl_b32 s26, s26, 8
	s_add_i32 s26, s26, s72
	s_cmp_lg_u32 s31, s26
	s_cbranch_scc0 .LBB0_1060
